# NA: next unit's first loads (Q, K0..K2, V0, V1) issued before the last slot of the current unit; first unit's loads overlap the bias-table build
# speedup vs baseline: 1.0086x; 1.0041x over previous
.Lna_noremap:
	s_and_b32 s11, s8, 1
	v_and_b32_e32 v216, 31, v0
	v_bfe_u32 v217, v0, 5, 1
	v_mov_b32_e32 v228, 0
	v_mov_b32_e32 v229, 0xf149f2ca
	s_lshl_b32 s36, s11, 5
	v_add_u32_e32 v222, s36, v216
	v_mul_u32_u24_e32 v199, 0x90, v222
	v_lshl_add_u32 v199, v217, 4, v199
	s_cmp_eq_u32 s11, 0
	s_cselect_b32 s37, 0, 24
	s_cselect_b32 s38, 32, 0
	v_add_u32_e32 v222, s37, v216
	v_and_b32_e32 v222, 31, v222
	v_add_u32_e32 v222, s38, v222
	v_mul_u32_u24_e32 v200, 0x90, v222
	v_lshl_add_u32 v200, v217, 4, v200
	v_mul_u32_u24_e32 v222, 0x88, v216
	v_lshl_add_u32 v222, v217, 3, v222
	v_add_u32_e32 v222, 0x4800, v222
	s_lshl_b32 s36, s11, 6
	v_add_u32_e32 v201, s36, v222
	s_cmp_eq_u32 s11, 0
	s_cselect_b32 s37, 64, 48
	s_cselect_b32 s38, 0x50, 0
	v_add_u32_e32 v202, s37, v222
	v_add_u32_e32 v203, s38, v222
	v_lshrrev_b32_e32 v222, 3, v0
	v_and_b32_e32 v223, 7, v0
	v_mul_u32_u24_e32 v204, 0x90, v222
	v_lshl_add_u32 v204, v223, 4, v204
	v_mul_u32_u24_e32 v205, 0x88, v222
	v_lshl_add_u32 v205, v223, 4, v205
	v_add_u32_e32 v205, 0x4800, v205
	v_lshlrev_b32_e32 v206, 4, v0
	v_mul_u32_u24_e32 v207, 0x2200, v222
	v_lshl_add_u32 v207, v223, 4, v207
	v_lshl_or_b32 v222, s8, 5, v216
	v_lshlrev_b32_e32 v219, 7, v222
	v_lshl_add_u32 v219, v217, 4, v219
	v_lshlrev_b32_e32 v218, 10, v222
	v_lshl_add_u32 v218, v217, 3, v218
	v_and_b32_e32 v222, 3, v216
	v_add_u32_e32 v223, 1, v222
	v_and_b32_e32 v223, 3, v223
	v_lshl_add_u32 v223, v217, 2, v223
	v_sub_u32_e32 v223, v223, v216
	v_add_u32_e32 v223, 39, v223
	v_lshlrev_b32_e32 v223, 2, v223
	v_mul_u32_u24_e32 v222, 5040, v222
	v_add_u32_e32 v208, v222, v223
	v_add_u32_e32 v208, 0x8c00, v208
	s_cmp_eq_u32 s11, 0
	s_mov_b32 s37, 0x80
	s_cselect_b32 s37, s37, 0xffffffe0
	v_add_u32_e32 v209, s37, v208
	v_mov_b32_e32 v186, 0
	v_mov_b32_e32 v187, 0
	s_lshr_b32 s36, s10, 4
	s_and_b32 s37, s10, 15
	s_mul_i32 s38, s36, 0x88000
	s_add_u32 s38, s38, 0x4700000
	s_add_u32 s12, s4, s38
	s_addc_u32 s13, s5, 0
	s_add_u32 s38, s38, 0x1100000
	s_add_u32 s14, s4, s38
	s_addc_u32 s15, s5, 0
	s_add_u32 s16, s12, 0x80000
	s_addc_u32 s17, s13, 0
	s_add_u32 s18, s14, 0x2000
	s_addc_u32 s19, s15, 0
	s_lshr_b32 s40, s8, 1
	s_add_i32 s41, s40, 1
	s_add_i32 s38, s37, -1
	s_cmp_lt_u32 s38, 14
	s_cselect_b32 s22, 12, 8
	s_cselect_b32 s39, 1, 0
	s_cselect_b32 s23, s41, 0
	s_lshl_b32 s41, s37, 2
	s_add_i32 s42, s41, -4
	s_max_i32 s42, s42, 0
	s_min_i32 s42, s42, 56
	s_sub_i32 s42, s42, s39
	s_add_i32 s43, s41, s40
	s_sub_i32 s43, s42, s43
	s_add_i32 s43, s43, 7
	s_mul_i32 s25, s43, 0x150
	s_ashr_i32 s43, s42, 31
	s_lshl_b64 s[44:45], s[42:43], 13
	s_add_u32 s12, s12, s44
	s_addc_u32 s13, s13, s45
	s_lshl_b64 s[44:45], s[42:43], 7
	s_add_u32 s14, s14, s44
	s_addc_u32 s15, s15, s45
	s_lshl_b32 s38, s36, 12
	s_lshl_b32 s39, s37, 8
	s_add_u32 s38, s38, s39
	s_lshl_b32 s38, s38, 7
	s_add_u32 s38, s38, 0x6900000
	s_add_u32 s34, s4, s38
	s_addc_u32 s35, s5, 0
	s_lshr_b32 s38, s36, 3
	s_lshl_b32 s38, s38, 12
	s_add_u32 s38, s38, s39
	s_lshl_b32 s38, s38, 10
	s_and_b32 s40, s36, 7
	s_lshl_b32 s40, s40, 7
	s_add_u32 s38, s38, s40
	s_add_u32 s38, s38, 0x8900000
	s_add_u32 s30, s4, s38
	s_addc_u32 s31, s5, 0
	global_load_dwordx4 v[98:101], v219, s[34:35] offset:0
	global_load_dwordx4 v[102:105], v219, s[34:35] offset:32
	global_load_dwordx4 v[106:109], v219, s[34:35] offset:64
	global_load_dwordx4 v[110:113], v219, s[34:35] offset:96
	global_load_dwordx4 v[34:37], v206, s[12:13]
	s_add_u32 s12, s12, 0x2000
	s_addc_u32 s13, s13, 0
	global_load_dwordx4 v[230:233], v206, s[12:13]
	global_load_dwordx4 v[234:237], v207, s[14:15]
	s_add_u32 s12, s12, 0x2000
	s_addc_u32 s13, s13, 0
	s_add_u32 s14, s14, 0x80
	s_addc_u32 s15, s15, 0
	global_load_dwordx4 v[188:191], v206, s[12:13]
	global_load_dwordx4 v[192:195], v207, s[14:15]
	s_add_u32 s12, s12, 0x2000
	s_addc_u32 s13, s13, 0
	s_add_u32 s14, s14, 0x80
	s_addc_u32 s15, s15, 0
	s_mov_b32 s20, 3
	s_mov_b32 s21, 2
	s_lshr_b32 s36, s10, 4
	s_and_b32 s36, s36, 7
	s_mul_i32 s36, s36, 0x744
	s_add_u32 s38, s6, s36
	s_addc_u32 s39, s7, 0
	s_mov_b32 s36, 0xd00e
	v_mov_b32_e32 v222, v0
	v_mul_lo_u32 v223, v222, s36
	v_lshrrev_b32_e32 v223, 26, v223
	v_mul_u32_u24_e32 v224, 1260, v223
	v_sub_u32_e32 v224, v222, v224
	v_mul_u32_u24_e32 v225, 49933, v224
	v_lshrrev_b32_e32 v225, 22, v225
	v_mul_u32_u24_e32 v226, 84, v225
	v_sub_u32_e32 v226, v224, v226
	v_add_u32_e32 v227, 1, v223
	v_and_b32_e32 v227, 3, v227
	v_sub_u32_e32 v226, v226, v227
	v_subrev_u32_e32 v226, 24, v226
	v_cmp_gt_u32_e64 s[40:41], 31, v226
	s_nop 1
	v_cndmask_b32_e64 v227, 0, v226, s[40:41]
	v_mad_u32_u24 v227, v225, 31, v227
	v_lshlrev_b32_e32 v227, 2, v227
	global_load_dword v40, v227, s[38:39]
	v_add_u32_e32 v222, 512, v0
	v_mul_lo_u32 v223, v222, s36
	v_lshrrev_b32_e32 v223, 26, v223
	v_mul_u32_u24_e32 v224, 1260, v223
	v_sub_u32_e32 v224, v222, v224
	v_mul_u32_u24_e32 v225, 49933, v224
	v_lshrrev_b32_e32 v225, 22, v225
	v_mul_u32_u24_e32 v226, 84, v225
	v_sub_u32_e32 v226, v224, v226
	v_add_u32_e32 v227, 1, v223
	v_and_b32_e32 v227, 3, v227
	v_sub_u32_e32 v226, v226, v227
	v_subrev_u32_e32 v226, 24, v226
	v_cmp_gt_u32_e64 s[42:43], 31, v226
	s_nop 1
	v_cndmask_b32_e64 v227, 0, v226, s[42:43]
	v_mad_u32_u24 v227, v225, 31, v227
	v_lshlrev_b32_e32 v227, 2, v227
	global_load_dword v41, v227, s[38:39]
	v_add_u32_e32 v222, 1024, v0
	v_mul_lo_u32 v223, v222, s36
	v_lshrrev_b32_e32 v223, 26, v223
	v_mul_u32_u24_e32 v224, 1260, v223
	v_sub_u32_e32 v224, v222, v224
	v_mul_u32_u24_e32 v225, 49933, v224
	v_lshrrev_b32_e32 v225, 22, v225
	v_mul_u32_u24_e32 v226, 84, v225
	v_sub_u32_e32 v226, v224, v226
	v_add_u32_e32 v227, 1, v223
	v_and_b32_e32 v227, 3, v227
	v_sub_u32_e32 v226, v226, v227
	v_subrev_u32_e32 v226, 24, v226
	v_cmp_gt_u32_e64 s[44:45], 31, v226
	s_nop 1
	v_cndmask_b32_e64 v227, 0, v226, s[44:45]
	v_mad_u32_u24 v227, v225, 31, v227
	v_lshlrev_b32_e32 v227, 2, v227
	global_load_dword v42, v227, s[38:39]
	v_add_u32_e32 v222, 1536, v0
	v_mul_lo_u32 v223, v222, s36
	v_lshrrev_b32_e32 v223, 26, v223
	v_mul_u32_u24_e32 v224, 1260, v223
	v_sub_u32_e32 v224, v222, v224
	v_mul_u32_u24_e32 v225, 49933, v224
	v_lshrrev_b32_e32 v225, 22, v225
	v_mul_u32_u24_e32 v226, 84, v225
	v_sub_u32_e32 v226, v224, v226
	v_add_u32_e32 v227, 1, v223
	v_and_b32_e32 v227, 3, v227
	v_sub_u32_e32 v226, v226, v227
	v_subrev_u32_e32 v226, 24, v226
	v_cmp_gt_u32_e64 s[46:47], 31, v226
	s_nop 1
	v_cndmask_b32_e64 v227, 0, v226, s[46:47]
	v_mad_u32_u24 v227, v225, 31, v227
	v_lshlrev_b32_e32 v227, 2, v227
	global_load_dword v43, v227, s[38:39]
	v_add_u32_e32 v222, 2048, v0
	v_mul_lo_u32 v223, v222, s36
	v_lshrrev_b32_e32 v223, 26, v223
	v_mul_u32_u24_e32 v224, 1260, v223
	v_sub_u32_e32 v224, v222, v224
	v_mul_u32_u24_e32 v225, 49933, v224
	v_lshrrev_b32_e32 v225, 22, v225
	v_mul_u32_u24_e32 v226, 84, v225
	v_sub_u32_e32 v226, v224, v226
	v_add_u32_e32 v227, 1, v223
	v_and_b32_e32 v227, 3, v227
	v_sub_u32_e32 v226, v226, v227
	v_subrev_u32_e32 v226, 24, v226
	v_cmp_gt_u32_e64 s[48:49], 31, v226
	s_nop 1
	v_cndmask_b32_e64 v227, 0, v226, s[48:49]
	v_mad_u32_u24 v227, v225, 31, v227
	v_lshlrev_b32_e32 v227, 2, v227
	global_load_dword v44, v227, s[38:39]
	v_add_u32_e32 v222, 2560, v0
	v_mul_lo_u32 v223, v222, s36
	v_lshrrev_b32_e32 v223, 26, v223
	v_mul_u32_u24_e32 v224, 1260, v223
	v_sub_u32_e32 v224, v222, v224
	v_mul_u32_u24_e32 v225, 49933, v224
	v_lshrrev_b32_e32 v225, 22, v225
	v_mul_u32_u24_e32 v226, 84, v225
	v_sub_u32_e32 v226, v224, v226
	v_add_u32_e32 v227, 1, v223
	v_and_b32_e32 v227, 3, v227
	v_sub_u32_e32 v226, v226, v227
	v_subrev_u32_e32 v226, 24, v226
	v_cmp_gt_u32_e64 s[50:51], 31, v226
	s_nop 1
	v_cndmask_b32_e64 v227, 0, v226, s[50:51]
	v_mad_u32_u24 v227, v225, 31, v227
	v_lshlrev_b32_e32 v227, 2, v227
	global_load_dword v45, v227, s[38:39]
	v_add_u32_e32 v222, 3072, v0
	v_mul_lo_u32 v223, v222, s36
	v_lshrrev_b32_e32 v223, 26, v223
	v_mul_u32_u24_e32 v224, 1260, v223
	v_sub_u32_e32 v224, v222, v224
	v_mul_u32_u24_e32 v225, 49933, v224
	v_lshrrev_b32_e32 v225, 22, v225
	v_mul_u32_u24_e32 v226, 84, v225
	v_sub_u32_e32 v226, v224, v226
	v_add_u32_e32 v227, 1, v223
	v_and_b32_e32 v227, 3, v227
	v_sub_u32_e32 v226, v226, v227
	v_subrev_u32_e32 v226, 24, v226
	v_cmp_gt_u32_e64 s[52:53], 31, v226
	s_nop 1
	v_cndmask_b32_e64 v227, 0, v226, s[52:53]
	v_mad_u32_u24 v227, v225, 31, v227
	v_lshlrev_b32_e32 v227, 2, v227
	global_load_dword v46, v227, s[38:39]
	v_add_u32_e32 v222, 3584, v0
	v_mul_lo_u32 v223, v222, s36
	v_lshrrev_b32_e32 v223, 26, v223
	v_mul_u32_u24_e32 v224, 1260, v223
	v_sub_u32_e32 v224, v222, v224
	v_mul_u32_u24_e32 v225, 49933, v224
	v_lshrrev_b32_e32 v225, 22, v225
	v_mul_u32_u24_e32 v226, 84, v225
	v_sub_u32_e32 v226, v224, v226
	v_add_u32_e32 v227, 1, v223
	v_and_b32_e32 v227, 3, v227
	v_sub_u32_e32 v226, v226, v227
	v_subrev_u32_e32 v226, 24, v226
	v_cmp_gt_u32_e64 s[54:55], 31, v226
	s_nop 1
	v_cndmask_b32_e64 v227, 0, v226, s[54:55]
	v_mad_u32_u24 v227, v225, 31, v227
	v_lshlrev_b32_e32 v227, 2, v227
	global_load_dword v47, v227, s[38:39]
	v_add_u32_e32 v222, 4096, v0
	v_mul_lo_u32 v223, v222, s36
	v_lshrrev_b32_e32 v223, 26, v223
	v_mul_u32_u24_e32 v224, 1260, v223
	v_sub_u32_e32 v224, v222, v224
	v_mul_u32_u24_e32 v225, 49933, v224
	v_lshrrev_b32_e32 v225, 22, v225
	v_mul_u32_u24_e32 v226, 84, v225
	v_sub_u32_e32 v226, v224, v226
	v_add_u32_e32 v227, 1, v223
	v_and_b32_e32 v227, 3, v227
	v_sub_u32_e32 v226, v226, v227
	v_subrev_u32_e32 v226, 24, v226
	v_cmp_gt_u32_e64 s[56:57], 31, v226
	s_nop 1
	v_cndmask_b32_e64 v227, 0, v226, s[56:57]
	v_mad_u32_u24 v227, v225, 31, v227
	v_lshlrev_b32_e32 v227, 2, v227
	global_load_dword v48, v227, s[38:39]
	v_add_u32_e32 v222, 4608, v0
	v_mul_lo_u32 v223, v222, s36
	v_lshrrev_b32_e32 v223, 26, v223
	v_mul_u32_u24_e32 v224, 1260, v223
	v_sub_u32_e32 v224, v222, v224
	v_mul_u32_u24_e32 v225, 49933, v224
	v_lshrrev_b32_e32 v225, 22, v225
	v_mul_u32_u24_e32 v226, 84, v225
	v_sub_u32_e32 v226, v224, v226
	v_add_u32_e32 v227, 1, v223
	v_and_b32_e32 v227, 3, v227
	v_sub_u32_e32 v226, v226, v227
	v_subrev_u32_e32 v226, 24, v226
	v_cmp_gt_u32_e64 s[58:59], 31, v226
	s_nop 1
	v_cndmask_b32_e64 v227, 0, v226, s[58:59]
	v_mad_u32_u24 v227, v225, 31, v227
	v_lshlrev_b32_e32 v227, 2, v227
	global_load_dword v49, v227, s[38:39]
	v_lshlrev_b32_e32 v222, 2, v0
	s_waitcnt vmcnt(0)
	v_mul_f32_e32 v40, 0x3fb8aa3b, v40
	v_cndmask_b32_e64 v40, 0, v40, s[40:41]
	v_mul_f32_e32 v41, 0x3fb8aa3b, v41
	v_cndmask_b32_e64 v41, 0, v41, s[42:43]
	v_mul_f32_e32 v42, 0x3fb8aa3b, v42
	v_cndmask_b32_e64 v42, 0, v42, s[44:45]
	v_mul_f32_e32 v43, 0x3fb8aa3b, v43
	v_cndmask_b32_e64 v43, 0, v43, s[46:47]
	v_mul_f32_e32 v44, 0x3fb8aa3b, v44
	v_cndmask_b32_e64 v44, 0, v44, s[48:49]
	v_mul_f32_e32 v45, 0x3fb8aa3b, v45
	v_cndmask_b32_e64 v45, 0, v45, s[50:51]
	v_mul_f32_e32 v46, 0x3fb8aa3b, v46
	v_cndmask_b32_e64 v46, 0, v46, s[52:53]
	v_mul_f32_e32 v47, 0x3fb8aa3b, v47
	v_cndmask_b32_e64 v47, 0, v47, s[54:55]
	v_mul_f32_e32 v48, 0x3fb8aa3b, v48
	v_cndmask_b32_e64 v48, 0, v48, s[56:57]
	v_mul_f32_e32 v49, 0x3fb8aa3b, v49
	v_cndmask_b32_e64 v49, 0, v49, s[58:59]
	v_cmp_gt_u32_e32 vcc, 432, v0
	ds_write_b32 v222, v40 offset:35840
	ds_write_b32 v222, v41 offset:37888
	ds_write_b32 v222, v42 offset:39936
	ds_write_b32 v222, v43 offset:41984
	ds_write_b32 v222, v44 offset:44032
	ds_write_b32 v222, v45 offset:46080
	ds_write_b32 v222, v46 offset:48128
	ds_write_b32 v222, v47 offset:50176
	ds_write_b32 v222, v48 offset:52224
	s_and_saveexec_b64 s[60:61], vcc
	ds_write_b32 v222, v49 offset:54272
	s_mov_b64 exec, s[60:61]
	v_mov_b32_e32 v2, 0
	v_mov_b32_e32 v3, 0
	v_mov_b32_e32 v4, 0
	v_mov_b32_e32 v5, 0
	v_mov_b32_e32 v6, 0
	v_mov_b32_e32 v7, 0
	v_mov_b32_e32 v8, 0
	v_mov_b32_e32 v9, 0
	v_mov_b32_e32 v10, 0
	v_mov_b32_e32 v11, 0
	v_mov_b32_e32 v12, 0
	v_mov_b32_e32 v13, 0
	v_mov_b32_e32 v14, 0
	v_mov_b32_e32 v15, 0
	v_mov_b32_e32 v16, 0
	v_mov_b32_e32 v17, 0
	v_mov_b32_e32 v18, 0
	v_mov_b32_e32 v19, 0
	v_mov_b32_e32 v20, 0
	v_mov_b32_e32 v21, 0
	v_mov_b32_e32 v22, 0
	v_mov_b32_e32 v23, 0
	v_mov_b32_e32 v24, 0
	v_mov_b32_e32 v25, 0
	v_mov_b32_e32 v26, 0
	v_mov_b32_e32 v27, 0
	v_mov_b32_e32 v28, 0
	v_mov_b32_e32 v29, 0
	v_mov_b32_e32 v30, 0
	v_mov_b32_e32 v31, 0
	v_mov_b32_e32 v32, 0
	v_mov_b32_e32 v33, 0
	v_mov_b32_e32 v212, 0
	v_mov_b32_e32 v213, 0
	v_mov_b32_e32 v214, 0
	v_mov_b32_e32 v220, 0xff7fffff
	v_mov_b32_e32 v221, 0
	s_mov_b64 s[26:27], -1
	v_and_b32_e32 v216, 31, v0
	v_bfe_u32 v217, v0, 5, 1
	s_lshl_b32 s36, s11, 5
	v_add_u32_e32 v222, s36, v216
	v_subrev_u32_e32 v223, 8, v222
	v_med3_i32 v223, v223, 0, 48
	v_lshl_add_u32 v224, v217, 2, s36
	v_sub_u32_e32 v224, v224, v223
	v_add_u32_e32 v225, 0, v224
	v_cmp_gt_u32_e32 vcc, 16, v225
	s_nop 1
	v_cndmask_b32_e32 v114, v229, v228, vcc
	v_add_u32_e32 v225, 1, v224
	v_cmp_gt_u32_e32 vcc, 16, v225
	s_nop 1
	v_cndmask_b32_e32 v115, v229, v228, vcc
	v_add_u32_e32 v225, 2, v224
	v_cmp_gt_u32_e32 vcc, 16, v225
	s_nop 1
	v_cndmask_b32_e32 v116, v229, v228, vcc
	v_add_u32_e32 v225, 3, v224
	v_cmp_gt_u32_e32 vcc, 16, v225
	s_nop 1
	v_cndmask_b32_e32 v117, v229, v228, vcc
	v_add_u32_e32 v225, 8, v224
	v_cmp_gt_u32_e32 vcc, 16, v225
	s_nop 1
	v_cndmask_b32_e32 v118, v229, v228, vcc
	v_add_u32_e32 v225, 9, v224
	v_cmp_gt_u32_e32 vcc, 16, v225
	s_nop 1
	v_cndmask_b32_e32 v119, v229, v228, vcc
	v_add_u32_e32 v225, 10, v224
	v_cmp_gt_u32_e32 vcc, 16, v225
	s_nop 1
	v_cndmask_b32_e32 v120, v229, v228, vcc
	v_add_u32_e32 v225, 11, v224
	v_cmp_gt_u32_e32 vcc, 16, v225
	s_nop 1
	v_cndmask_b32_e32 v121, v229, v228, vcc
	v_add_u32_e32 v225, 16, v224
	v_cmp_gt_u32_e32 vcc, 16, v225
	s_nop 1
	v_cndmask_b32_e32 v122, v229, v228, vcc
	v_add_u32_e32 v225, 17, v224
	v_cmp_gt_u32_e32 vcc, 16, v225
	s_nop 1
	v_cndmask_b32_e32 v123, v229, v228, vcc
	v_add_u32_e32 v225, 18, v224
	v_cmp_gt_u32_e32 vcc, 16, v225
	s_nop 1
	v_cndmask_b32_e32 v124, v229, v228, vcc
	v_add_u32_e32 v225, 19, v224
	v_cmp_gt_u32_e32 vcc, 16, v225
	s_nop 1
	v_cndmask_b32_e32 v125, v229, v228, vcc
	v_add_u32_e32 v225, 24, v224
	v_cmp_gt_u32_e32 vcc, 16, v225
	s_nop 1
	v_cndmask_b32_e32 v126, v229, v228, vcc
	v_add_u32_e32 v225, 25, v224
	v_cmp_gt_u32_e32 vcc, 16, v225
	s_nop 1
	v_cndmask_b32_e32 v127, v229, v228, vcc
	v_add_u32_e32 v225, 26, v224
	v_cmp_gt_u32_e32 vcc, 16, v225
	s_nop 1
	v_cndmask_b32_e32 v128, v229, v228, vcc
	v_add_u32_e32 v225, 27, v224
	v_cmp_gt_u32_e32 vcc, 16, v225
	s_nop 1
	v_cndmask_b32_e32 v129, v229, v228, vcc
	s_cmp_eq_u32 s11, 0
	s_cselect_b32 s37, 32, 24
	v_lshl_add_u32 v224, v217, 2, s37
	v_sub_u32_e32 v224, v224, v223
	v_add_u32_e32 v225, 0, v224
	v_cmp_gt_u32_e32 vcc, 16, v225
	s_nop 1
	v_cndmask_b32_e32 v130, v229, v228, vcc
	v_add_u32_e32 v225, 1, v224
	v_cmp_gt_u32_e32 vcc, 16, v225
	s_nop 1
	v_cndmask_b32_e32 v131, v229, v228, vcc
	v_add_u32_e32 v225, 2, v224
	v_cmp_gt_u32_e32 vcc, 16, v225
	s_nop 1
	v_cndmask_b32_e32 v132, v229, v228, vcc
	v_add_u32_e32 v225, 3, v224
	v_cmp_gt_u32_e32 vcc, 16, v225
	s_nop 1
	v_cndmask_b32_e32 v133, v229, v228, vcc
	v_mov_b32_e32 v134, 0
	v_mov_b32_e32 v135, 0
	v_mov_b32_e32 v136, 0
	v_mov_b32_e32 v137, 0
	v_mov_b32_e32 v138, 0
	v_mov_b32_e32 v139, 0
	v_mov_b32_e32 v140, 0
	v_mov_b32_e32 v141, 0
	v_mov_b32_e32 v142, 0
	v_mov_b32_e32 v143, 0
	v_mov_b32_e32 v144, 0
	v_mov_b32_e32 v145, 0
.Lna_stage:
	ds_write_b128 v204, v[34:37]
	s_waitcnt lgkmcnt(0)
	s_barrier
	s_mov_b32 s24, -1
	s_lshr_b32 s33, s22, 1

.Lna_nr_c2:
	s_waitcnt lgkmcnt(0)
	s_barrier
	global_load_dwordx2 v[146:147], v218, s[30:31] offset:0
	global_load_dwordx2 v[148:149], v218, s[30:31] offset:16
	global_load_dwordx2 v[150:151], v218, s[30:31] offset:32
	global_load_dwordx2 v[152:153], v218, s[30:31] offset:48
	global_load_dwordx2 v[154:155], v218, s[30:31] offset:64
	global_load_dwordx2 v[156:157], v218, s[30:31] offset:80
	global_load_dwordx2 v[158:159], v218, s[30:31] offset:96
	global_load_dwordx2 v[160:161], v218, s[30:31] offset:112
	s_mov_b64 s[46:47], s[30:31]
	s_add_i32 s10, s10, s9
	s_cmpk_lt_i32 s10, 0x200
	s_cbranch_scc0 .Lna_nopf
	s_lshr_b32 s36, s10, 4
	s_and_b32 s37, s10, 15
	s_mul_i32 s38, s36, 0x88000
	s_add_u32 s38, s38, 0x4700000
	s_add_u32 s12, s4, s38
	s_addc_u32 s13, s5, 0
	s_add_u32 s38, s38, 0x1100000
	s_add_u32 s14, s4, s38
	s_addc_u32 s15, s5, 0
	s_add_u32 s16, s12, 0x80000
	s_addc_u32 s17, s13, 0
	s_add_u32 s18, s14, 0x2000
	s_addc_u32 s19, s15, 0
	s_lshr_b32 s40, s8, 1
	s_add_i32 s41, s40, 1
	s_add_i32 s38, s37, -1
	s_cmp_lt_u32 s38, 14
	s_cselect_b32 s22, 12, 8
	s_cselect_b32 s39, 1, 0
	s_cselect_b32 s23, s41, 0
	s_lshl_b32 s41, s37, 2
	s_add_i32 s42, s41, -4
	s_max_i32 s42, s42, 0
	s_min_i32 s42, s42, 56
	s_sub_i32 s42, s42, s39
	s_add_i32 s43, s41, s40
	s_sub_i32 s43, s42, s43
	s_add_i32 s43, s43, 7
	s_mul_i32 s25, s43, 0x150
	s_ashr_i32 s43, s42, 31
	s_lshl_b64 s[44:45], s[42:43], 13
	s_add_u32 s12, s12, s44
	s_addc_u32 s13, s13, s45
	s_lshl_b64 s[44:45], s[42:43], 7
	s_add_u32 s14, s14, s44
	s_addc_u32 s15, s15, s45
	s_lshl_b32 s38, s36, 12
	s_lshl_b32 s39, s37, 8
	s_add_u32 s38, s38, s39
	s_lshl_b32 s38, s38, 7
	s_add_u32 s38, s38, 0x6900000
	s_add_u32 s34, s4, s38
	s_addc_u32 s35, s5, 0
	s_lshr_b32 s38, s36, 3
	s_lshl_b32 s38, s38, 12
	s_add_u32 s38, s38, s39
	s_lshl_b32 s38, s38, 10
	s_and_b32 s40, s36, 7
	s_lshl_b32 s40, s40, 7
	s_add_u32 s38, s38, s40
	s_add_u32 s38, s38, 0x8900000
	s_add_u32 s30, s4, s38
	s_addc_u32 s31, s5, 0
	global_load_dwordx4 v[98:101], v219, s[34:35] offset:0
	global_load_dwordx4 v[102:105], v219, s[34:35] offset:32
	global_load_dwordx4 v[106:109], v219, s[34:35] offset:64
	global_load_dwordx4 v[110:113], v219, s[34:35] offset:96
	global_load_dwordx4 v[34:37], v206, s[12:13]
	s_add_u32 s12, s12, 0x2000
	s_addc_u32 s13, s13, 0
	global_load_dwordx4 v[230:233], v206, s[12:13]
	global_load_dwordx4 v[234:237], v207, s[14:15]
	s_add_u32 s12, s12, 0x2000
	s_addc_u32 s13, s13, 0
	s_add_u32 s14, s14, 0x80
	s_addc_u32 s15, s15, 0
	global_load_dwordx4 v[188:191], v206, s[12:13]
	global_load_dwordx4 v[192:195], v207, s[14:15]
	s_add_u32 s12, s12, 0x2000
	s_addc_u32 s13, s13, 0
	s_add_u32 s14, s14, 0x80
	s_addc_u32 s15, s15, 0
	s_mov_b32 s20, 3
	s_mov_b32 s21, 2
.Lna_nopf:
	v_exp_f32_e32 v66, v66
	v_exp_f32_e32 v67, v67
	v_exp_f32_e32 v68, v68
	v_exp_f32_e32 v69, v69
	v_add_f32_e32 v213, v213, v66
	v_add_f32_e32 v214, v214, v67
	v_add_f32_e32 v213, v213, v68
	v_add_f32_e32 v214, v214, v69
	v_exp_f32_e32 v70, v70
	ds_read_b64 v[162:163], v201 offset:8704
	ds_read_b64 v[164:165], v201 offset:8720
	ds_read_b64 v[166:167], v201 offset:13056
	ds_read_b64 v[168:169], v201 offset:13072
	ds_read_b64 v[170:171], v201 offset:8736
	ds_read_b64 v[172:173], v201 offset:8752
	ds_read_b64 v[174:175], v201 offset:13088
	ds_read_b64 v[176:177], v201 offset:13104
	v_exp_f32_e32 v71, v71
	v_exp_f32_e32 v72, v72
	v_exp_f32_e32 v73, v73
	v_add_f32_e32 v213, v213, v70
	v_add_f32_e32 v214, v214, v71
	v_add_f32_e32 v213, v213, v72
	v_add_f32_e32 v214, v214, v73
	v_cvt_pk_bf16_f32 v66, v66, v67
	v_cvt_pk_bf16_f32 v67, v68, v69
	v_cvt_pk_bf16_f32 v68, v70, v71
	v_cvt_pk_bf16_f32 v69, v72, v73
	s_waitcnt lgkmcnt(6)
	s_nop 0
	v_mfma_f32_32x32x16_bf16 v[2:17], v[162:165], v[66:69], v[2:17]
	ds_read_b64 v[162:163], v202 offset:8704
	ds_read_b64 v[164:165], v203 offset:8704
	s_waitcnt lgkmcnt(6)
	v_mfma_f32_32x32x16_bf16 v[18:33], v[166:169], v[66:69], v[18:33]
	ds_read_b64 v[166:167], v202 offset:13056
	ds_read_b64 v[168:169], v203 offset:13056
	v_exp_f32_e32 v74, v74
	v_exp_f32_e32 v75, v75
	v_exp_f32_e32 v76, v76
	v_exp_f32_e32 v77, v77
	v_add_f32_e32 v213, v213, v74
	v_add_f32_e32 v214, v214, v75
	v_add_f32_e32 v213, v213, v76
	v_add_f32_e32 v214, v214, v77
	v_exp_f32_e32 v78, v78
	v_exp_f32_e32 v79, v79
	v_exp_f32_e32 v80, v80
	v_exp_f32_e32 v81, v81
	v_add_f32_e32 v213, v213, v78
	v_add_f32_e32 v214, v214, v79
	v_add_f32_e32 v213, v213, v80
	v_add_f32_e32 v214, v214, v81
	v_cvt_pk_bf16_f32 v74, v74, v75
	v_cvt_pk_bf16_f32 v75, v76, v77
	v_cvt_pk_bf16_f32 v76, v78, v79
	v_cvt_pk_bf16_f32 v77, v80, v81
	s_waitcnt lgkmcnt(6)
	s_nop 0
	v_mfma_f32_32x32x16_bf16 v[2:17], v[170:173], v[74:77], v[2:17]
	ds_read_b64 v[170:171], v203 offset:8720
	ds_read_b64 v[172:173], v203 offset:8736
	s_waitcnt lgkmcnt(6)
	v_mfma_f32_32x32x16_bf16 v[18:33], v[174:177], v[74:77], v[18:33]
	ds_read_b64 v[174:175], v203 offset:13072
	ds_read_b64 v[176:177], v203 offset:13088
	v_exp_f32_e32 v82, v82
	v_exp_f32_e32 v83, v83
	v_exp_f32_e32 v84, v84
	v_exp_f32_e32 v85, v85
	v_add_f32_e32 v213, v213, v82
	v_add_f32_e32 v214, v214, v83
	v_add_f32_e32 v213, v213, v84
	v_add_f32_e32 v214, v214, v85
	v_exp_f32_e32 v86, v86
	v_exp_f32_e32 v87, v87
	v_exp_f32_e32 v88, v88
	v_exp_f32_e32 v89, v89
	v_add_f32_e32 v213, v213, v86
	v_add_f32_e32 v214, v214, v87
	v_add_f32_e32 v213, v213, v88
	v_add_f32_e32 v214, v214, v89
	v_cvt_pk_bf16_f32 v82, v82, v83
	v_cvt_pk_bf16_f32 v83, v84, v85
	v_cvt_pk_bf16_f32 v84, v86, v87
	v_cvt_pk_bf16_f32 v85, v88, v89
	s_waitcnt lgkmcnt(6)
	s_nop 0
	v_mfma_f32_32x32x16_bf16 v[2:17], v[162:165], v[82:85], v[2:17]
	s_waitcnt lgkmcnt(4)
	v_mfma_f32_32x32x16_bf16 v[18:33], v[166:169], v[82:85], v[18:33]
	v_exp_f32_e32 v90, v90
	v_exp_f32_e32 v91, v91
	v_exp_f32_e32 v92, v92
	v_exp_f32_e32 v93, v93
	v_add_f32_e32 v213, v213, v90
	v_add_f32_e32 v214, v214, v91
	v_add_f32_e32 v213, v213, v92
	v_add_f32_e32 v214, v214, v93
	v_exp_f32_e32 v94, v94
	v_exp_f32_e32 v95, v95
	v_exp_f32_e32 v96, v96
	v_exp_f32_e32 v97, v97
	v_add_f32_e32 v213, v213, v94
	v_add_f32_e32 v214, v214, v95
	v_add_f32_e32 v213, v213, v96
	v_add_f32_e32 v214, v214, v97
	v_cvt_pk_bf16_f32 v90, v90, v91
	v_cvt_pk_bf16_f32 v91, v92, v93
	v_cvt_pk_bf16_f32 v92, v94, v95
	v_cvt_pk_bf16_f32 v93, v96, v97
	s_waitcnt lgkmcnt(2)
	s_nop 0
	v_mfma_f32_32x32x16_bf16 v[2:17], v[170:173], v[90:93], v[2:17]
	s_waitcnt lgkmcnt(0)
	v_mfma_f32_32x32x16_bf16 v[18:33], v[174:177], v[90:93], v[18:33]
	s_waitcnt lgkmcnt(0)
	s_barrier
	v_add_f32_e32 v213, v213, v214
	v_mov_b32_e32 v217, v213
	s_nop 1
	v_permlane32_swap_b32_e32 v213, v217
	v_add_f32_e32 v216, v213, v217
	v_div_scale_f32 v217, s[36:37], v216, v216, 1.0
	v_rcp_f32_e32 v223, v217
	v_div_scale_f32 v224, vcc, 1.0, v216, 1.0
	v_fma_f32 v225, -v217, v223, 1.0
	v_fmac_f32_e32 v223, v225, v223
	v_mul_f32_e32 v225, v224, v223
	v_fma_f32 v226, -v217, v225, v224
	v_fmac_f32_e32 v225, v226, v223
	v_fma_f32 v217, -v217, v225, v224
	v_div_fmas_f32 v217, v217, v223, v225
	v_div_fixup_f32 v216, v217, v216, 1.0
	s_nop 15
	v_mul_f32_e32 v2, v2, v216
	v_mul_f32_e32 v3, v3, v216
	v_mul_f32_e32 v4, v4, v216
	v_mul_f32_e32 v5, v5, v216
	v_mul_f32_e32 v6, v6, v216
	v_mul_f32_e32 v7, v7, v216
	v_mul_f32_e32 v8, v8, v216
	v_mul_f32_e32 v9, v9, v216
	v_mul_f32_e32 v10, v10, v216
	v_mul_f32_e32 v11, v11, v216
	v_mul_f32_e32 v12, v12, v216
	v_mul_f32_e32 v13, v13, v216
	v_mul_f32_e32 v14, v14, v216
	v_mul_f32_e32 v15, v15, v216
	v_mul_f32_e32 v16, v16, v216
	v_mul_f32_e32 v17, v17, v216
	v_mul_f32_e32 v18, v18, v216
	v_mul_f32_e32 v19, v19, v216
	v_mul_f32_e32 v20, v20, v216
	v_mul_f32_e32 v21, v21, v216
	v_mul_f32_e32 v22, v22, v216
	v_mul_f32_e32 v23, v23, v216
	v_mul_f32_e32 v24, v24, v216
	v_mul_f32_e32 v25, v25, v216
	v_mul_f32_e32 v26, v26, v216
	v_mul_f32_e32 v27, v27, v216
	v_mul_f32_e32 v28, v28, v216
	v_mul_f32_e32 v29, v29, v216
	v_mul_f32_e32 v30, v30, v216
	v_mul_f32_e32 v31, v31, v216
	v_mul_f32_e32 v32, v32, v216
	v_mul_f32_e32 v33, v33, v216
	s_cmpk_lt_i32 s10, 0x200
	s_cbranch_scc1 .Lna_zw9
	s_waitcnt vmcnt(0)
	s_branch .Lna_zw
.Lna_zw9:
	s_waitcnt vmcnt(9)
.Lna_zw:
	v_lshlrev_b32_e32 v223, 16, v146
	v_and_b32_e32 v224, 0xffff0000, v146
	v_lshlrev_b32_e32 v225, 16, v147
	v_and_b32_e32 v226, 0xffff0000, v147
	v_mul_f32_e32 v2, v2, v223
	v_mul_f32_e32 v3, v3, v224
	v_mul_f32_e32 v4, v4, v225
	v_mul_f32_e32 v5, v5, v226
	v_cvt_pk_bf16_f32 v146, v2, v3
	v_cvt_pk_bf16_f32 v147, v4, v5
	global_store_dwordx2 v218, v[146:147], s[46:47] offset:0
	v_lshlrev_b32_e32 v223, 16, v148
	v_and_b32_e32 v224, 0xffff0000, v148
	v_lshlrev_b32_e32 v225, 16, v149
	v_and_b32_e32 v226, 0xffff0000, v149
	v_mul_f32_e32 v6, v6, v223
	v_mul_f32_e32 v7, v7, v224
	v_mul_f32_e32 v8, v8, v225
	v_mul_f32_e32 v9, v9, v226
	v_cvt_pk_bf16_f32 v148, v6, v7
	v_cvt_pk_bf16_f32 v149, v8, v9
	global_store_dwordx2 v218, v[148:149], s[46:47] offset:16
	v_lshlrev_b32_e32 v223, 16, v150
	v_and_b32_e32 v224, 0xffff0000, v150
	v_lshlrev_b32_e32 v225, 16, v151
	v_and_b32_e32 v226, 0xffff0000, v151
	v_mul_f32_e32 v10, v10, v223
	v_mul_f32_e32 v11, v11, v224
	v_mul_f32_e32 v12, v12, v225
	v_mul_f32_e32 v13, v13, v226
	v_cvt_pk_bf16_f32 v150, v10, v11
	v_cvt_pk_bf16_f32 v151, v12, v13
	global_store_dwordx2 v218, v[150:151], s[46:47] offset:32
	v_lshlrev_b32_e32 v223, 16, v152
	v_and_b32_e32 v224, 0xffff0000, v152
	v_lshlrev_b32_e32 v225, 16, v153
	v_and_b32_e32 v226, 0xffff0000, v153
	v_mul_f32_e32 v14, v14, v223
	v_mul_f32_e32 v15, v15, v224
	v_mul_f32_e32 v16, v16, v225
	v_mul_f32_e32 v17, v17, v226
	v_cvt_pk_bf16_f32 v152, v14, v15
	v_cvt_pk_bf16_f32 v153, v16, v17
	global_store_dwordx2 v218, v[152:153], s[46:47] offset:48
	v_lshlrev_b32_e32 v223, 16, v154
	v_and_b32_e32 v224, 0xffff0000, v154
	v_lshlrev_b32_e32 v225, 16, v155
	v_and_b32_e32 v226, 0xffff0000, v155
	v_mul_f32_e32 v18, v18, v223
	v_mul_f32_e32 v19, v19, v224
	v_mul_f32_e32 v20, v20, v225
	v_mul_f32_e32 v21, v21, v226
	v_cvt_pk_bf16_f32 v154, v18, v19
	v_cvt_pk_bf16_f32 v155, v20, v21
	global_store_dwordx2 v218, v[154:155], s[46:47] offset:64
	v_lshlrev_b32_e32 v223, 16, v156
	v_and_b32_e32 v224, 0xffff0000, v156
	v_lshlrev_b32_e32 v225, 16, v157
	v_and_b32_e32 v226, 0xffff0000, v157
	v_mul_f32_e32 v22, v22, v223
	v_mul_f32_e32 v23, v23, v224
	v_mul_f32_e32 v24, v24, v225
	v_mul_f32_e32 v25, v25, v226
	v_cvt_pk_bf16_f32 v156, v22, v23
	v_cvt_pk_bf16_f32 v157, v24, v25
	global_store_dwordx2 v218, v[156:157], s[46:47] offset:80
	v_lshlrev_b32_e32 v223, 16, v158
	v_and_b32_e32 v224, 0xffff0000, v158
	v_lshlrev_b32_e32 v225, 16, v159
	v_and_b32_e32 v226, 0xffff0000, v159
	v_mul_f32_e32 v26, v26, v223
	v_mul_f32_e32 v27, v27, v224
	v_mul_f32_e32 v28, v28, v225
	v_mul_f32_e32 v29, v29, v226
	v_cvt_pk_bf16_f32 v158, v26, v27
	v_cvt_pk_bf16_f32 v159, v28, v29
	global_store_dwordx2 v218, v[158:159], s[46:47] offset:96
	v_lshlrev_b32_e32 v223, 16, v160
	v_and_b32_e32 v224, 0xffff0000, v160
	v_lshlrev_b32_e32 v225, 16, v161
	v_and_b32_e32 v226, 0xffff0000, v161
	v_mul_f32_e32 v30, v30, v223
	v_mul_f32_e32 v31, v31, v224
	v_mul_f32_e32 v32, v32, v225
	v_mul_f32_e32 v33, v33, v226
	v_cvt_pk_bf16_f32 v160, v30, v31
	v_cvt_pk_bf16_f32 v161, v32, v33
	global_store_dwordx2 v218, v[160:161], s[46:47] offset:112
	s_cmpk_lt_i32 s10, 0x200
	s_cbranch_scc0 .Lna_exit
	v_mov_b32_e32 v2, 0
	v_mov_b32_e32 v3, 0
	v_mov_b32_e32 v4, 0
	v_mov_b32_e32 v5, 0
	v_mov_b32_e32 v6, 0
	v_mov_b32_e32 v7, 0
	v_mov_b32_e32 v8, 0
	v_mov_b32_e32 v9, 0
	v_mov_b32_e32 v10, 0
	v_mov_b32_e32 v11, 0
	v_mov_b32_e32 v12, 0
	v_mov_b32_e32 v13, 0
	v_mov_b32_e32 v14, 0
	v_mov_b32_e32 v15, 0
	v_mov_b32_e32 v16, 0
	v_mov_b32_e32 v17, 0
	v_mov_b32_e32 v18, 0
	v_mov_b32_e32 v19, 0
	v_mov_b32_e32 v20, 0
	v_mov_b32_e32 v21, 0
	v_mov_b32_e32 v22, 0
	v_mov_b32_e32 v23, 0
	v_mov_b32_e32 v24, 0
	v_mov_b32_e32 v25, 0
	v_mov_b32_e32 v26, 0
	v_mov_b32_e32 v27, 0
	v_mov_b32_e32 v28, 0
	v_mov_b32_e32 v29, 0
	v_mov_b32_e32 v30, 0
	v_mov_b32_e32 v31, 0
	v_mov_b32_e32 v32, 0
	v_mov_b32_e32 v33, 0
	v_mov_b32_e32 v212, 0
	v_mov_b32_e32 v213, 0
	v_mov_b32_e32 v214, 0
	v_mov_b32_e32 v220, 0xff7fffff
	v_mov_b32_e32 v221, 0
	s_mov_b64 s[26:27], -1
	v_and_b32_e32 v216, 31, v0
	v_bfe_u32 v217, v0, 5, 1
	s_lshl_b32 s36, s11, 5
	v_add_u32_e32 v222, s36, v216
	v_subrev_u32_e32 v223, 8, v222
	v_med3_i32 v223, v223, 0, 48
	v_lshl_add_u32 v224, v217, 2, s36
	v_sub_u32_e32 v224, v224, v223
	v_add_u32_e32 v225, 0, v224
	v_cmp_gt_u32_e32 vcc, 16, v225
	s_nop 1
	v_cndmask_b32_e32 v114, v229, v228, vcc
	v_add_u32_e32 v225, 1, v224
	v_cmp_gt_u32_e32 vcc, 16, v225
	s_nop 1
	v_cndmask_b32_e32 v115, v229, v228, vcc
	v_add_u32_e32 v225, 2, v224
	v_cmp_gt_u32_e32 vcc, 16, v225
	s_nop 1
	v_cndmask_b32_e32 v116, v229, v228, vcc
	v_add_u32_e32 v225, 3, v224
	v_cmp_gt_u32_e32 vcc, 16, v225
	s_nop 1
	v_cndmask_b32_e32 v117, v229, v228, vcc
	v_add_u32_e32 v225, 8, v224
	v_cmp_gt_u32_e32 vcc, 16, v225
	s_nop 1
	v_cndmask_b32_e32 v118, v229, v228, vcc
	v_add_u32_e32 v225, 9, v224
	v_cmp_gt_u32_e32 vcc, 16, v225
	s_nop 1
	v_cndmask_b32_e32 v119, v229, v228, vcc
	v_add_u32_e32 v225, 10, v224
	v_cmp_gt_u32_e32 vcc, 16, v225
	s_nop 1
	v_cndmask_b32_e32 v120, v229, v228, vcc
	v_add_u32_e32 v225, 11, v224
	v_cmp_gt_u32_e32 vcc, 16, v225
	s_nop 1
	v_cndmask_b32_e32 v121, v229, v228, vcc
	v_add_u32_e32 v225, 16, v224
	v_cmp_gt_u32_e32 vcc, 16, v225
	s_nop 1
	v_cndmask_b32_e32 v122, v229, v228, vcc
	v_add_u32_e32 v225, 17, v224
	v_cmp_gt_u32_e32 vcc, 16, v225
	s_nop 1
	v_cndmask_b32_e32 v123, v229, v228, vcc
	v_add_u32_e32 v225, 18, v224
	v_cmp_gt_u32_e32 vcc, 16, v225
	s_nop 1
	v_cndmask_b32_e32 v124, v229, v228, vcc
	v_add_u32_e32 v225, 19, v224
	v_cmp_gt_u32_e32 vcc, 16, v225
	s_nop 1
	v_cndmask_b32_e32 v125, v229, v228, vcc
	v_add_u32_e32 v225, 24, v224
	v_cmp_gt_u32_e32 vcc, 16, v225
	s_nop 1
	v_cndmask_b32_e32 v126, v229, v228, vcc
	v_add_u32_e32 v225, 25, v224
	v_cmp_gt_u32_e32 vcc, 16, v225
	s_nop 1
	v_cndmask_b32_e32 v127, v229, v228, vcc
	v_add_u32_e32 v225, 26, v224
	v_cmp_gt_u32_e32 vcc, 16, v225
	s_nop 1
	v_cndmask_b32_e32 v128, v229, v228, vcc
	v_add_u32_e32 v225, 27, v224
	v_cmp_gt_u32_e32 vcc, 16, v225
	s_nop 1
	v_cndmask_b32_e32 v129, v229, v228, vcc
	s_cmp_eq_u32 s11, 0
	s_cselect_b32 s37, 32, 24
	v_lshl_add_u32 v224, v217, 2, s37
	v_sub_u32_e32 v224, v224, v223
	v_add_u32_e32 v225, 0, v224
	v_cmp_gt_u32_e32 vcc, 16, v225
	s_nop 1
	v_cndmask_b32_e32 v130, v229, v228, vcc
	v_add_u32_e32 v225, 1, v224
	v_cmp_gt_u32_e32 vcc, 16, v225
	s_nop 1
	v_cndmask_b32_e32 v131, v229, v228, vcc
	v_add_u32_e32 v225, 2, v224
	v_cmp_gt_u32_e32 vcc, 16, v225
	s_nop 1
	v_cndmask_b32_e32 v132, v229, v228, vcc
	v_add_u32_e32 v225, 3, v224
	v_cmp_gt_u32_e32 vcc, 16, v225
	s_nop 1
	v_cndmask_b32_e32 v133, v229, v228, vcc
	v_mov_b32_e32 v134, 0
	v_mov_b32_e32 v135, 0
	v_mov_b32_e32 v136, 0
	v_mov_b32_e32 v137, 0
	v_mov_b32_e32 v138, 0
	v_mov_b32_e32 v139, 0
	v_mov_b32_e32 v140, 0
	v_mov_b32_e32 v141, 0
	v_mov_b32_e32 v142, 0
	v_mov_b32_e32 v143, 0
	v_mov_b32_e32 v144, 0
	v_mov_b32_e32 v145, 0
	s_waitcnt vmcnt(12)
	s_branch .Lna_stage
.Lna_exit:
	s_mov_b32 s88, s9
